# MoE gate/up tile prologue: weight loads issued right after idx loads, before the idx wait
# speedup vs baseline: 1.0035x; 1.0035x over previous
.LBB0_1184:
	s_ashr_i32 s2, s17, 31
	s_lshr_b32 s2, s2, 25
	s_add_i32 s3, s17, s2
	s_ashr_i32 s2, s3, 7
	s_and_b32 s3, s3, 0xff80
	s_sub_i32 s3, s17, s3
	s_bfe_i32 s4, s3, 0x80000
	s_bfe_u32 s4, s4, 0x2000d
	s_add_i32 s4, s3, s4
	s_bfe_i32 s8, s4, 0x80000
	s_and_b32 s4, s4, 0xfc
	s_sub_i32 s3, s3, s4
	s_lshl_b32 s4, s2, 10
	s_ashr_i32 s5, s4, 31
	s_lshl_b64 s[4:5], s[4:5], 2
	s_sext_i32_i8 s3, s3
	s_add_u32 s9, s68, s4
	s_addc_u32 s10, s69, s5
	s_lshl_b32 s4, s3, 8
	s_ashr_i32 s5, s4, 31
	s_lshl_b64 s[6:7], s[4:5], 2
	v_mov_b32_e32 v252, v250
	s_add_u32 s6, s9, s6
	s_addc_u32 s7, s10, s7
	v_ashrrev_i32_e32 v0, 3, v252
	v_ashrrev_i32_e32 v1, 31, v0
	v_lshl_add_u64 v[0:1], v[0:1], 2, s[6:7]
	global_load_dword v2, v[0:1], off
	global_load_dword v4, v[0:1], off offset:128
	global_load_dword v6, v[0:1], off offset:256
	global_load_dword v8, v[0:1], off offset:384
	global_load_dword v10, v[0:1], off offset:512
	global_load_dword v14, v[0:1], off offset:640
	global_load_dword v15, v[0:1], off offset:768
	global_load_dword v17, v[0:1], off offset:896
	s_sext_i32_i16 s5, s8
	s_lshl_b32 s5, s5, 4
	s_ashr_i32 s3, s2, 31
	s_and_b32 s6, s5, 0xffffffc0
	v_readlane_b32 s76, v254, 50
	s_lshl_b64 s[8:9], s[2:3], 21
	s_lshl_b64 s[10:11], s[2:3], 23
	s_ashr_i32 s7, s6, 31
	v_readlane_b32 s86, v254, 60
	v_readlane_b32 s87, v254, 61
	s_add_u32 s5, s86, s10
	v_and_b32_e32 v22, 31, v252
	v_ashrrev_i32_e32 v23, 5, v252
	s_addc_u32 s19, s87, s11
	s_lshl_b64 s[2:3], s[6:7], 2
	v_lshlrev_b32_e32 v25, 4, v252
	v_lshlrev_b32_e32 v26, 2, v22
	v_lshlrev_b32_e32 v12, 3, v23
	s_add_u32 s18, s5, s2
	v_mov_b32_e32 v1, v193
	v_lshlrev_b32_e32 v27, 1, v22
	v_and_b32_e32 v0, 0x70, v25
	v_and_b32_e32 v16, 28, v26
	v_ashrrev_i32_e32 v13, 31, v12
	s_addc_u32 s19, s19, s3
	v_mov_b32_e32 v3, v193
	v_bfe_u32 v24, v252, 3, 1
	v_lshl_add_u64 v[194:195], s[64:65], 0, v[0:1]
	v_and_or_b32 v16, v27, 32, v16
	v_lshlrev_b64 v[0:1], 13, v[12:13]
	v_mov_b64_e32 v[12:13], s[18:19]
	s_waitcnt vmcnt(8)
	v_mov_b32_e32 v5, v193
	v_mov_b32_e32 v7, v193
	v_mov_b32_e32 v9, v193
	v_mov_b32_e32 v11, v193
	v_mul_lo_u32 v28, s13, v24
	v_lshlrev_b32_e32 v192, 2, v16
	v_mad_u64_u32 v[12:13], s[18:19], s12, v24, v[12:13]
	v_add_u32_e32 v13, v28, v13
	v_lshl_add_u64 v[12:13], v[12:13], 0, v[192:193]
	v_mov_b32_e32 v19, v193
	v_lshl_add_u64 v[12:13], v[12:13], 0, v[0:1]
	global_load_dwordx4 v[176:179], v[12:13], off
	v_add_co_u32_e32 v226, vcc, s14, v12
	s_nop 1
	v_addc_co_u32_e32 v227, vcc, 0, v13, vcc
	v_add_co_u32_e32 v228, vcc, s15, v12
	s_nop 1
	v_addc_co_u32_e32 v229, vcc, 0, v13, vcc
	global_load_dwordx4 v[160:163], v[226:227], off
	global_load_dwordx4 v[164:167], v[228:229], off
	v_add_co_u32_e32 v226, vcc, s16, v12
	s_nop 1
	v_addc_co_u32_e32 v227, vcc, 0, v13, vcc
	v_add_co_u32_e32 v228, vcc, 0x8000, v12
	s_nop 1
	v_addc_co_u32_e32 v229, vcc, 0, v13, vcc
	global_load_dwordx4 v[168:171], v[226:227], off
	global_load_dwordx4 v[172:175], v[228:229], off
	v_add_co_u32_e32 v226, vcc, 0xa000, v12
	s_nop 1
	v_addc_co_u32_e32 v227, vcc, 0, v13, vcc
	v_add_co_u32_e32 v228, vcc, 0xc000, v12
	s_nop 1
	v_addc_co_u32_e32 v229, vcc, 0, v13, vcc
	global_load_dwordx4 v[180:183], v[226:227], off
	global_load_dwordx4 v[184:187], v[228:229], off
	v_add_co_u32_e32 v226, vcc, 0xe000, v12
	s_nop 1
	v_addc_co_u32_e32 v227, vcc, 0, v13, vcc
	global_load_dwordx4 v[188:191], v[226:227], off
	s_mov_b32 s5, 0x8000
	v_lshrrev_b32_e32 v20, 4, v252
	v_and_b32_e32 v218, 15, v252
	v_bfe_u32 v21, v252, 4, 2
	v_bfe_u32 v251, v252, 6, 1
	v_mov_b32_e32 v32, 0
	v_mov_b32_e32 v33, v193
	v_mov_b32_e32 v34, v193
	v_mov_b32_e32 v35, v193
	v_mov_b32_e32 v40, 0
	v_mov_b32_e32 v41, v193
	v_mov_b32_e32 v42, v193
	v_mov_b32_e32 v43, v193
	v_mov_b32_e32 v36, 0
	v_mov_b32_e32 v37, v193
	v_mov_b32_e32 v38, v193
	v_mov_b32_e32 v39, v193
	v_mov_b32_e32 v44, 0
	v_mov_b32_e32 v45, v193
	v_mov_b32_e32 v46, v193
	v_mov_b32_e32 v47, v193
	v_mov_b32_e32 v48, 0
	v_mov_b32_e32 v49, v193
	v_mov_b32_e32 v50, v193
	v_mov_b32_e32 v51, v193
	v_mov_b32_e32 v56, 0
	v_mov_b32_e32 v57, v193
	v_mov_b32_e32 v58, v193
	v_mov_b32_e32 v59, v193
	s_waitcnt vmcnt(15)
	v_lshlrev_b32_e32 v2, 10, v2
	s_waitcnt vmcnt(14)
	v_lshlrev_b32_e32 v4, 10, v4
	s_waitcnt vmcnt(13)
	v_lshlrev_b32_e32 v6, 10, v6
	s_waitcnt vmcnt(12)
	v_lshlrev_b32_e32 v8, 10, v8
	s_waitcnt vmcnt(11)
	v_lshlrev_b32_e32 v10, 10, v10
	s_waitcnt vmcnt(10)
	v_lshlrev_b32_e32 v14, 10, v14
	s_waitcnt vmcnt(9)
	v_lshlrev_b32_e32 v16, 10, v15
	v_lshlrev_b64 v[196:197], 1, v[2:3]
	v_mov_b32_e32 v15, v193
	s_waitcnt vmcnt(8)
	v_lshlrev_b32_e32 v18, 10, v17
	v_lshlrev_b64 v[198:199], 1, v[4:5]
	v_lshlrev_b64 v[200:201], 1, v[6:7]
	v_lshlrev_b64 v[202:203], 1, v[8:9]
	v_lshlrev_b64 v[204:205], 1, v[10:11]
	v_lshl_add_u64 v[2:3], v[194:195], 0, v[196:197]
	v_lshlrev_b64 v[206:207], 1, v[14:15]
	v_mov_b32_e32 v17, v193
	v_lshl_add_u64 v[4:5], v[194:195], 0, v[198:199]
	v_lshl_add_u64 v[6:7], v[194:195], 0, v[200:201]
	v_lshl_add_u64 v[8:9], v[194:195], 0, v[202:203]
	v_lshl_add_u64 v[10:11], v[194:195], 0, v[204:205]
	global_load_dwordx4 v[120:123], v[2:3], off
	global_load_dwordx4 v[124:127], v[4:5], off
	global_load_dwordx4 v[128:131], v[6:7], off
	global_load_dwordx4 v[132:135], v[8:9], off
	v_lshl_add_u64 v[2:3], v[194:195], 0, v[206:207]
	v_lshlrev_b64 v[208:209], 1, v[16:17]
	global_load_dwordx4 v[136:139], v[10:11], off
	global_load_dwordx4 v[140:143], v[2:3], off
	v_lshl_add_u64 v[2:3], v[194:195], 0, v[208:209]
	v_lshlrev_b64 v[210:211], 1, v[18:19]
	v_lshl_add_u64 v[4:5], v[194:195], 0, v[210:211]
	global_load_dwordx4 v[144:147], v[2:3], off
	global_load_dwordx4 v[152:155], v[4:5], off
	v_lshlrev_b32_e32 v6, 9, v22
	s_nop 0
	v_or_b32_e32 v196, 0x80, v196
	s_nop 0
	v_or_b32_e32 v198, 0x80, v198
	s_nop 0
	s_mov_b32 s5, 0xa000
	s_nop 0
	s_mov_b32 s5, 0xc000
	s_nop 0
	s_mov_b32 s5, 0xe000
	s_nop 0
	s_movk_i32 s5, 0x70
	s_nop 0
	v_bitop3_b32 v2, v27, v23, 6 bitop3:0x6c
	v_lshlrev_b32_e32 v7, 4, v2
	v_or_b32_e32 v2, 2, v26
	v_lshlrev_b32_e32 v8, 7, v2
	v_lshrrev_b32_e32 v2, 1, v2
	v_bitop3_b32 v2, v2, v23, 7 bitop3:0x6c
	v_lshlrev_b32_e32 v9, 4, v2
	v_or_b32_e32 v2, 3, v26
	v_lshlrev_b32_e32 v10, 7, v2
	v_lshrrev_b32_e32 v2, 1, v2
	v_bitop3_b32 v2, v2, v23, 7 bitop3:0x6c
	v_bfe_u32 v12, v252, 1, 3
	v_bitop3_b32 v5, v25, v252, s5 bitop3:0x28
	v_lshlrev_b32_e32 v11, 4, v2
	v_lshlrev_b32_e32 v2, 7, v252
	v_lshlrev_b32_e32 v3, 7, v218
	s_movk_i32 s5, 0xc000
	v_bitop3_b32 v13, v20, v12, 3 bitop3:0x6c
	v_bitop3_b32 v12, v21, v12, 4 bitop3:0x36
	v_and_or_b32 v2, v2, s5, v3
	v_lshl_or_b32 v3, v251, 13, v3
	v_lshlrev_b32_e32 v13, 4, v13
	v_lshlrev_b32_e32 v12, 4, v12
	v_or_b32_e32 v219, v3, v13
	v_or_b32_e32 v220, v2, v13
	v_or_b32_e32 v221, v3, v12
	v_or_b32_e32 v222, v2, v12
	v_mov_b64_e32 v[2:3], s[10:11]
	v_mad_u64_u32 v[2:3], s[10:11], s12, v24, v[2:3]
	v_add_u32_e32 v3, v28, v3
	v_lshl_add_u64 v[0:1], v[2:3], 0, v[0:1]
	v_lshl_add_u64 v[0:1], v[0:1], 0, s[2:3]
	v_and_b32_e32 v4, 0xffffff80, v25
	v_lshl_add_u64 v[0:1], v[0:1], 0, v[192:193]
	v_or_b32_e32 v200, 0x80, v200
	v_or_b32_e32 v202, 0x80, v202
	v_or_b32_e32 v204, 0x80, v204
	v_or_b32_e32 v206, 0x80, v206
	v_or_b32_e32 v208, 0x80, v208
	v_or_b32_e32 v210, 0x80, v210
	v_lshl_add_u64 v[212:213], s[0:1], 0, v[0:1]
	v_add_u32_e32 v192, v4, v5
	v_add_u32_e32 v223, v6, v7
	v_add_u32_e32 v224, v8, v9
	v_add_u32_e32 v225, v10, v11
	s_mov_b32 s5, 0
	v_mov_b32_e32 v52, 0
	v_mov_b32_e32 v53, v193
	v_mov_b32_e32 v54, v193
	v_mov_b32_e32 v55, v193
	v_mov_b32_e32 v60, 0
	v_mov_b32_e32 v61, v193
	v_mov_b32_e32 v62, v193
	v_mov_b32_e32 v63, v193
	v_mov_b32_e32 v64, 0
	v_mov_b32_e32 v65, v193
	v_mov_b32_e32 v66, v193
	v_mov_b32_e32 v67, v193
	v_mov_b32_e32 v72, 0
	v_mov_b32_e32 v73, v193
	v_mov_b32_e32 v74, v193
	v_mov_b32_e32 v75, v193
	v_mov_b32_e32 v68, 0
	v_mov_b32_e32 v69, v193
	v_mov_b32_e32 v70, v193
	v_mov_b32_e32 v71, v193
	v_mov_b32_e32 v76, 0
	v_mov_b32_e32 v77, v193
	v_mov_b32_e32 v78, v193
	v_mov_b32_e32 v79, v193
	v_mov_b32_e32 v80, 0
	v_mov_b32_e32 v81, v193
	v_mov_b32_e32 v82, v193
	v_mov_b32_e32 v83, v193
	v_mov_b32_e32 v88, 0
	v_mov_b32_e32 v89, v193
	v_mov_b32_e32 v90, v193
	v_mov_b32_e32 v91, v193
	v_mov_b32_e32 v84, 0
	v_mov_b32_e32 v85, v193
	v_mov_b32_e32 v86, v193
	v_mov_b32_e32 v87, v193
	v_mov_b32_e32 v92, 0
	v_mov_b32_e32 v93, v193
	v_mov_b32_e32 v94, v193
	v_mov_b32_e32 v95, v193
	v_mov_b32_e32 v96, 0
	v_mov_b32_e32 v97, v193
	v_mov_b32_e32 v98, v193
	v_mov_b32_e32 v99, v193
	v_mov_b32_e32 v104, 0
	v_mov_b32_e32 v105, v193
	v_mov_b32_e32 v106, v193
	v_mov_b32_e32 v107, v193
	v_mov_b32_e32 v100, 0
	v_mov_b32_e32 v101, v193
	v_mov_b32_e32 v102, v193
	v_mov_b32_e32 v103, v193
	v_mov_b32_e32 v108, 0
	v_mov_b32_e32 v109, v193
	v_mov_b32_e32 v110, v193
	v_mov_b32_e32 v111, v193
	v_mov_b32_e32 v112, 0
	v_mov_b32_e32 v113, v193
	v_mov_b32_e32 v114, v193
	v_mov_b32_e32 v115, v193
	v_mov_b32_e32 v148, 0
	v_mov_b32_e32 v149, v193
	v_mov_b32_e32 v150, v193
	v_mov_b32_e32 v151, v193
	v_mov_b32_e32 v116, 0
	v_mov_b32_e32 v117, v193
	v_mov_b32_e32 v118, v193
	v_mov_b32_e32 v119, v193
	v_mov_b32_e32 v156, 0
	v_mov_b32_e32 v157, v193
	v_mov_b32_e32 v158, v193
	v_mov_b32_e32 v159, v193
	v_mov_b32_e32 v24, 0
	v_mov_b32_e32 v25, v193
	v_mov_b32_e32 v26, v193
	v_mov_b32_e32 v27, v193
	v_mov_b32_e32 v16, 0
	v_mov_b32_e32 v18, v193
	v_mov_b32_e32 v28, 0
	v_mov_b32_e32 v29, v193
	v_mov_b32_e32 v30, v193
	v_mov_b32_e32 v31, v193
	v_mov_b32_e32 v20, 0
	v_mov_b32_e32 v21, v193
	v_mov_b32_e32 v22, v193
	v_mov_b32_e32 v23, v193
	v_mov_b32_e32 v8, 0
	v_mov_b32_e32 v9, v193
	v_mov_b32_e32 v10, v193
	v_mov_b32_e32 v11, v193
	v_mov_b32_e32 v0, 0
	v_mov_b32_e32 v1, v193
	v_mov_b32_e32 v2, v193
	v_mov_b32_e32 v3, v193
	v_mov_b32_e32 v12, 0
	v_mov_b32_e32 v13, v193
	v_mov_b32_e32 v14, v193
	v_mov_b32_e32 v4, 0
	v_mov_b32_e32 v5, v193
	v_mov_b32_e32 v6, v193
	v_mov_b32_e32 v7, v193
	v_readlane_b32 s77, v254, 51
	v_readlane_b32 s78, v254, 52
	v_readlane_b32 s79, v254, 53
	v_readlane_b32 s80, v254, 54
	v_readlane_b32 s81, v254, 55
	v_readlane_b32 s82, v254, 56
	v_readlane_b32 s83, v254, 57
	v_readlane_b32 s84, v254, 58
	v_readlane_b32 s85, v254, 59
	v_readlane_b32 s88, v254, 62
	v_readlane_b32 s89, v254, 63
	v_readlane_b32 s90, v253, 0
	v_readlane_b32 s91, v253, 1
	s_branch .LBB0_1186

.LBB0_2217:
	s_ashr_i32 s6, s27, 31
	s_lshr_b32 s6, s6, 25
	s_add_i32 s6, s27, s6
	s_ashr_i32 s8, s6, 7
	s_and_b32 s6, s6, 0xff80
	s_sub_i32 s6, s27, s6
	s_bfe_i32 s7, s6, 0x80000
	s_bfe_u32 s7, s7, 0x2000d
	s_add_i32 s7, s6, s7
	s_bfe_i32 s9, s7, 0x80000
	s_and_b32 s7, s7, 0xfc
	s_sub_i32 s6, s6, s7
	s_sext_i32_i8 s10, s6
	s_lshl_b32 s6, s8, 10
	s_ashr_i32 s7, s6, 31
	s_lshl_b64 s[6:7], s[6:7], 2
	s_add_u32 s12, s68, s6
	s_addc_u32 s13, s69, s7
	s_lshl_b32 s6, s10, 8
	s_ashr_i32 s7, s6, 31
	s_lshl_b64 s[10:11], s[6:7], 2
	v_mov_b32_e32 v252, v250
	s_add_u32 s10, s12, s10
	s_addc_u32 s11, s13, s11
	v_ashrrev_i32_e32 v0, 3, v252
	v_ashrrev_i32_e32 v1, 31, v0
	v_lshl_add_u64 v[0:1], v[0:1], 2, s[10:11]
	global_load_dword v2, v[0:1], off
	global_load_dword v4, v[0:1], off offset:128
	global_load_dword v6, v[0:1], off offset:256
	global_load_dword v8, v[0:1], off offset:384
	global_load_dword v10, v[0:1], off offset:512
	global_load_dword v14, v[0:1], off offset:640
	global_load_dword v15, v[0:1], off offset:768
	global_load_dword v17, v[0:1], off offset:896
	s_sext_i32_i16 s7, s9
	s_lshl_b32 s7, s7, 4
	s_ashr_i32 s9, s8, 31
	s_and_b32 s12, s7, 0xffffffc0
	v_readlane_b32 s48, v254, 50
	s_lshl_b64 s[14:15], s[8:9], 23
	s_ashr_i32 s13, s12, 31
	v_readlane_b32 s58, v254, 60
	v_readlane_b32 s59, v254, 61
	s_add_u32 s7, s58, s14
	s_addc_u32 s28, s59, s15
	s_lshl_b64 s[10:11], s[12:13], 2
	s_add_u32 s7, s7, s10
	v_ashrrev_i32_e32 v23, 5, v252
	s_addc_u32 s13, s28, s11
	v_and_b32_e32 v22, 31, v252
	v_lshlrev_b32_e32 v25, 4, v252
	v_lshlrev_b32_e32 v12, 3, v23
	s_add_u32 s28, s7, 0x8000000
	v_mov_b32_e32 v1, v193
	v_lshlrev_b32_e32 v26, 2, v22
	v_and_b32_e32 v0, 0x70, v25
	v_ashrrev_i32_e32 v13, 31, v12
	s_addc_u32 s29, s13, 0
	v_mov_b32_e32 v3, v193
	v_bfe_u32 v24, v252, 3, 1
	v_lshlrev_b32_e32 v27, 1, v22
	v_and_b32_e32 v16, 28, v26
	v_lshl_add_u64 v[194:195], s[64:65], 0, v[0:1]
	v_lshlrev_b64 v[0:1], 13, v[12:13]
	v_mov_b64_e32 v[12:13], s[28:29]
	s_waitcnt vmcnt(8)
	v_mov_b32_e32 v5, v193
	v_mov_b32_e32 v7, v193
	v_mov_b32_e32 v9, v193
	v_mov_b32_e32 v11, v193
	v_mul_lo_u32 v28, s17, v24
	v_and_or_b32 v16, v27, 32, v16
	v_mad_u64_u32 v[12:13], s[28:29], s16, v24, v[12:13]
	v_lshlrev_b32_e32 v192, 2, v16
	v_add_u32_e32 v13, v28, v13
	v_lshl_add_u64 v[12:13], v[12:13], 0, v[192:193]
	v_mov_b32_e32 v19, v193
	v_lshl_add_u64 v[12:13], v[12:13], 0, v[0:1]
	global_load_dwordx4 v[156:159], v[12:13], off
	v_add_co_u32_e32 v226, vcc, s19, v12
	s_nop 1
	v_addc_co_u32_e32 v227, vcc, 0, v13, vcc
	v_add_co_u32_e32 v228, vcc, s20, v12
	s_nop 1
	v_addc_co_u32_e32 v229, vcc, 0, v13, vcc
	global_load_dwordx4 v[140:143], v[226:227], off
	global_load_dwordx4 v[148:151], v[228:229], off
	v_add_co_u32_e32 v226, vcc, s21, v12
	s_nop 1
	v_addc_co_u32_e32 v227, vcc, 0, v13, vcc
	v_add_co_u32_e32 v228, vcc, s22, v12
	s_nop 1
	v_addc_co_u32_e32 v229, vcc, 0, v13, vcc
	global_load_dwordx4 v[152:155], v[226:227], off
	global_load_dwordx4 v[160:163], v[228:229], off
	v_add_co_u32_e32 v226, vcc, s23, v12
	s_nop 1
	v_addc_co_u32_e32 v227, vcc, 0, v13, vcc
	v_add_co_u32_e32 v228, vcc, s24, v12
	s_nop 1
	v_addc_co_u32_e32 v229, vcc, 0, v13, vcc
	global_load_dwordx4 v[164:167], v[226:227], off
	global_load_dwordx4 v[168:171], v[228:229], off
	v_add_co_u32_e32 v226, vcc, s25, v12
	s_nop 1
	v_addc_co_u32_e32 v227, vcc, 0, v13, vcc
	global_load_dwordx4 v[172:175], v[226:227], off
	v_lshrrev_b32_e32 v20, 4, v252
	v_and_b32_e32 v251, 15, v252
	v_bfe_u32 v21, v252, 4, 2
	v_bfe_u32 v218, v252, 6, 1
	s_mov_b32 s7, 0
	v_mov_b32_e32 v40, 0
	v_mov_b32_e32 v41, v193
	v_mov_b32_e32 v42, v193
	v_mov_b32_e32 v43, v193
	v_mov_b32_e32 v29, v193
	v_mov_b32_e32 v30, v193
	v_mov_b32_e32 v31, v193
	v_mov_b32_e32 v44, 0
	v_mov_b32_e32 v45, v193
	v_mov_b32_e32 v46, v193
	v_mov_b32_e32 v47, v193
	v_mov_b32_e32 v48, 0
	v_mov_b32_e32 v49, v193
	v_mov_b32_e32 v50, v193
	v_mov_b32_e32 v51, v193
	v_mov_b32_e32 v56, 0
	v_mov_b32_e32 v57, v193
	v_mov_b32_e32 v58, v193
	v_mov_b32_e32 v59, v193
	v_mov_b32_e32 v52, 0
	v_mov_b32_e32 v53, v193
	v_mov_b32_e32 v54, v193
	v_mov_b32_e32 v55, v193
	s_waitcnt vmcnt(15)
	v_lshlrev_b32_e32 v2, 10, v2
	s_waitcnt vmcnt(14)
	v_lshlrev_b32_e32 v4, 10, v4
	s_waitcnt vmcnt(13)
	v_lshlrev_b32_e32 v6, 10, v6
	s_waitcnt vmcnt(12)
	v_lshlrev_b32_e32 v8, 10, v8
	s_waitcnt vmcnt(11)
	v_lshlrev_b32_e32 v10, 10, v10
	v_lshlrev_b64 v[196:197], 1, v[2:3]
	s_waitcnt vmcnt(10)
	v_lshlrev_b32_e32 v14, 10, v14
	s_waitcnt vmcnt(9)
	v_lshlrev_b32_e32 v16, 10, v15
	s_waitcnt vmcnt(8)
	v_lshlrev_b32_e32 v18, 10, v17
	v_lshlrev_b64 v[198:199], 1, v[4:5]
	v_lshlrev_b64 v[200:201], 1, v[6:7]
	v_lshlrev_b64 v[202:203], 1, v[8:9]
	v_lshlrev_b64 v[204:205], 1, v[10:11]
	v_lshl_add_u64 v[2:3], v[194:195], 0, v[196:197]
	v_mov_b32_e32 v15, v193
	v_mov_b32_e32 v17, v193
	v_lshl_add_u64 v[4:5], v[194:195], 0, v[198:199]
	v_lshl_add_u64 v[6:7], v[194:195], 0, v[200:201]
	v_lshl_add_u64 v[8:9], v[194:195], 0, v[202:203]
	global_load_dwordx4 v[100:103], v[2:3], off
	global_load_dwordx4 v[108:111], v[4:5], off
	global_load_dwordx4 v[112:115], v[6:7], off
	global_load_dwordx4 v[116:119], v[8:9], off
	v_lshl_add_u64 v[2:3], v[194:195], 0, v[204:205]
	v_lshlrev_b64 v[206:207], 1, v[14:15]
	v_lshlrev_b64 v[208:209], 1, v[16:17]
	v_lshl_add_u64 v[4:5], v[194:195], 0, v[206:207]
	global_load_dwordx4 v[120:123], v[2:3], off
	global_load_dwordx4 v[124:127], v[4:5], off
	v_lshl_add_u64 v[2:3], v[194:195], 0, v[208:209]
	v_lshlrev_b64 v[210:211], 1, v[18:19]
	v_lshl_add_u64 v[4:5], v[194:195], 0, v[210:211]
	global_load_dwordx4 v[128:131], v[2:3], off
	global_load_dwordx4 v[132:135], v[4:5], off
	v_lshlrev_b32_e32 v6, 9, v22
	s_nop 0
	v_or_b32_e32 v196, 0x80, v196
	s_nop 0
	v_or_b32_e32 v198, 0x80, v198
	s_nop 0
	v_or_b32_e32 v200, 0x80, v200
	s_nop 0
	v_or_b32_e32 v202, 0x80, v202
	s_nop 0
	v_or_b32_e32 v204, 0x80, v204
	s_nop 0
	v_bfe_u32 v12, v252, 1, 3
	s_nop 0
	v_bitop3_b32 v2, v27, v23, 6 bitop3:0x6c
	v_lshlrev_b32_e32 v7, 4, v2
	v_or_b32_e32 v2, 2, v26
	v_lshlrev_b32_e32 v8, 7, v2
	v_lshrrev_b32_e32 v2, 1, v2
	v_bitop3_b32 v2, v2, v23, 7 bitop3:0x6c
	v_lshlrev_b32_e32 v9, 4, v2
	v_or_b32_e32 v2, 3, v26
	v_lshlrev_b32_e32 v10, 7, v2
	v_lshrrev_b32_e32 v2, 1, v2
	v_bitop3_b32 v2, v2, v23, 7 bitop3:0x6c
	v_lshlrev_b32_e32 v11, 4, v2
	v_lshlrev_b32_e32 v2, 7, v252
	v_lshlrev_b32_e32 v3, 7, v251
	v_bitop3_b32 v13, v20, v12, 3 bitop3:0x6c
	v_bitop3_b32 v12, v21, v12, 4 bitop3:0x36
	v_and_or_b32 v2, v2, s26, v3
	v_lshl_or_b32 v3, v218, 13, v3
	v_lshlrev_b32_e32 v13, 4, v13
	v_lshlrev_b32_e32 v12, 4, v12
	v_or_b32_e32 v219, v3, v13
	v_or_b32_e32 v220, v2, v13
	v_or_b32_e32 v221, v3, v12
	v_or_b32_e32 v222, v2, v12
	v_mov_b64_e32 v[2:3], s[14:15]
	v_mad_u64_u32 v[2:3], s[14:15], s16, v24, v[2:3]
	v_add_u32_e32 v3, v28, v3
	v_lshl_add_u64 v[0:1], v[2:3], 0, v[0:1]
	v_lshl_add_u64 v[0:1], v[0:1], 0, s[10:11]
	v_and_b32_e32 v4, 0xffffff80, v25
	v_bitop3_b32 v5, v25, v252, s18 bitop3:0x28
	v_lshl_add_u64 v[0:1], v[0:1], 0, v[192:193]
	v_or_b32_e32 v206, 0x80, v206
	v_or_b32_e32 v208, 0x80, v208
	v_or_b32_e32 v210, 0x80, v210
	v_lshl_add_u64 v[212:213], s[0:1], 0, v[0:1]
	v_add_u32_e32 v192, v4, v5
	v_add_u32_e32 v223, v6, v7
	v_add_u32_e32 v224, v8, v9
	v_add_u32_e32 v225, v10, v11
	v_mov_b32_e32 v24, 0
	v_mov_b32_e32 v25, v193
	v_mov_b32_e32 v26, v193
	v_mov_b32_e32 v27, v193
	v_mov_b32_e32 v28, 0
	v_mov_b32_e32 v60, 0
	v_mov_b32_e32 v61, v193
	v_mov_b32_e32 v62, v193
	v_mov_b32_e32 v63, v193
	v_mov_b32_e32 v64, 0
	v_mov_b32_e32 v65, v193
	v_mov_b32_e32 v66, v193
	v_mov_b32_e32 v67, v193
	v_mov_b32_e32 v72, 0
	v_mov_b32_e32 v73, v193
	v_mov_b32_e32 v74, v193
	v_mov_b32_e32 v75, v193
	v_mov_b32_e32 v68, 0
	v_mov_b32_e32 v69, v193
	v_mov_b32_e32 v70, v193
	v_mov_b32_e32 v71, v193
	v_mov_b32_e32 v76, 0
	v_mov_b32_e32 v77, v193
	v_mov_b32_e32 v78, v193
	v_mov_b32_e32 v79, v193
	v_mov_b32_e32 v80, 0
	v_mov_b32_e32 v81, v193
	v_mov_b32_e32 v82, v193
	v_mov_b32_e32 v83, v193
	v_mov_b32_e32 v88, 0
	v_mov_b32_e32 v89, v193
	v_mov_b32_e32 v90, v193
	v_mov_b32_e32 v91, v193
	v_mov_b32_e32 v84, 0
	v_mov_b32_e32 v85, v193
	v_mov_b32_e32 v86, v193
	v_mov_b32_e32 v87, v193
	v_mov_b32_e32 v92, 0
	v_mov_b32_e32 v93, v193
	v_mov_b32_e32 v94, v193
	v_mov_b32_e32 v95, v193
	v_mov_b32_e32 v96, 0
	v_mov_b32_e32 v97, v193
	v_mov_b32_e32 v98, v193
	v_mov_b32_e32 v99, v193
	v_mov_b32_e32 v136, 0
	v_mov_b32_e32 v137, v193
	v_mov_b32_e32 v138, v193
	v_mov_b32_e32 v139, v193
	v_mov_b32_e32 v104, 0
	v_mov_b32_e32 v105, v193
	v_mov_b32_e32 v106, v193
	v_mov_b32_e32 v107, v193
	v_mov_b32_e32 v144, 0
	v_mov_b32_e32 v145, v193
	v_mov_b32_e32 v146, v193
	v_mov_b32_e32 v147, v193
	v_mov_b32_e32 v176, 0
	v_mov_b32_e32 v177, v193
	v_mov_b32_e32 v178, v193
	v_mov_b32_e32 v179, v193
	v_mov_b32_e32 v184, 0
	v_mov_b32_e32 v185, v193
	v_mov_b32_e32 v186, v193
	v_mov_b32_e32 v187, v193
	v_mov_b32_e32 v180, 0
	v_mov_b32_e32 v181, v193
	v_mov_b32_e32 v182, v193
	v_mov_b32_e32 v183, v193
	v_mov_b32_e32 v188, 0
	v_mov_b32_e32 v189, v193
	v_mov_b32_e32 v190, v193
	v_mov_b32_e32 v191, v193
	v_mov_b32_e32 v32, 0
	v_mov_b32_e32 v33, v193
	v_mov_b32_e32 v34, v193
	v_mov_b32_e32 v35, v193
	v_mov_b32_e32 v16, 0
	v_mov_b32_e32 v18, v193
	v_mov_b32_e32 v36, 0
	v_mov_b32_e32 v37, v193
	v_mov_b32_e32 v38, v193
	v_mov_b32_e32 v39, v193
	v_mov_b32_e32 v20, 0
	v_mov_b32_e32 v21, v193
	v_mov_b32_e32 v22, v193
	v_mov_b32_e32 v23, v193
	v_mov_b32_e32 v8, 0
	v_mov_b32_e32 v9, v193
	v_mov_b32_e32 v10, v193
	v_mov_b32_e32 v11, v193
	v_mov_b32_e32 v0, 0
	v_mov_b32_e32 v1, v193
	v_mov_b32_e32 v2, v193
	v_mov_b32_e32 v3, v193
	v_mov_b32_e32 v12, 0
	v_mov_b32_e32 v13, v193
	v_mov_b32_e32 v14, v193
	v_mov_b32_e32 v4, 0
	v_mov_b32_e32 v5, v193
	v_mov_b32_e32 v6, v193
	v_mov_b32_e32 v7, v193
	v_readlane_b32 s49, v254, 51
	v_readlane_b32 s50, v254, 52
	v_readlane_b32 s51, v254, 53
	v_readlane_b32 s52, v254, 54
	v_readlane_b32 s53, v254, 55
	v_readlane_b32 s54, v254, 56
	v_readlane_b32 s55, v254, 57
	v_readlane_b32 s56, v254, 58
	v_readlane_b32 s57, v254, 59
	v_readlane_b32 s60, v254, 62
	v_readlane_b32 s61, v254, 63
	v_readlane_b32 s62, v253, 0
	v_readlane_b32 s63, v253, 1
	s_branch .LBB0_2219
